# mixprep no longer writes the CKVN zero padding (unread since the kv up-projection runs K=128)
# speedup vs baseline: 1.0112x; 1.0000x over previous
; __device__ __forceinline__ unsigned pk2(float lo, float hi) { return pg8::cvt_pk_bf16(lo, hi); }
; __device__ __forceinline__ float bflo(unsigned u) { return (float)__builtin_bit_cast(f16x2, u).x; }
; __device__ __forceinline__ float bfhi(unsigned u) { return (float)__builtin_bit_cast(f16x2, u).y; }
; __device__ __forceinline__ void mixprep_rows(ArgP a, int l, int gw, int NGW, int lane) {
;     ...
;     for (int row0 = gw * 4; row0 < MTOT; row0 += NGW * 4) {
;         u32x2 ucq[4], unq[4], unk[4]; unsigned uckv[4];
; #pragma unroll
;         for (int t4 = 0; t4 < 4; ++t4) { const bf16_t* zr = Z + (size_t)(row0 + t4) * INW;
;             ucq[t4] = *(const u32x2*)(zr + Z_CQ + 4 * lane); uckv[t4] = *(const unsigned*)(zr + Z_CKV + 2 * lane);
;             unq[t4] = *(const u32x2*)(zr + Z_NQ + 4 * lane); unk[t4] = *(const u32x2*)(zr + Z_NK + 4 * lane); }
; #pragma unroll
;         for (int t4 = 0; t4 < 4; ++t4) {
;             const int row = row0 + t4; int b, p; if (row < MLAT) { b = row >> 13; p = 256 + (row & 8191); } else { b = (row - MLAT) >> 8; p = (row - MLAT) & 255; }
;             { const u32x2 u = ucq[t4]; float v0 = bflo(u.x), v1 = bfhi(u.x), v2 = bflo(u.y), v3 = bfhi(u.y);
;               const float rstd = 1.f / sqrtf(wave_sum(v0 * v0 + v1 * v1 + v2 * v2 + v3 * v3) * (1.f / 256) + EPS);
;               u32x2 o; o.x = pk2(v0 * rstd * gq.x, v1 * rstd * gq.y); o.y = pk2(v2 * rstd * gq.z, v3 * rstd * gq.w);
;               *(u32x2*)((bf16_t*)(a->ws + OFF_CQN) + (size_t)row * 256 + 4 * lane) = o; }
;             { const unsigned u = uckv[t4]; float v0 = bflo(u), v1 = bfhi(u);
;               const float rstd = 1.f / sqrtf(wave_sum(v0 * v0 + v1 * v1) * (1.f / 128) + EPS);
;               bf16_t* o = (bf16_t*)(a->ws + OFF_CKVN) + (size_t)row * 256;
;               *(unsigned*)(o + 2 * lane) = pk2(v0 * rstd * gkv0, v1 * rstd * gkv1); *(unsigned*)(o + 128 + 2 * lane) = 0u; }
.LBB0_768:
	v_lshl_add_u64 v[34:35], s[10:11], 0, v[30:31]
	v_add_co_u32_e32 v36, vcc, 0x7e00000, v34
	v_lshl_add_u64 v[62:63], s[10:11], 0, v[32:33]
	s_nop 0
	v_addc_co_u32_e32 v37, vcc, 0, v35, vcc
	global_load_dwordx2 v[42:43], v[36:37], off offset:1536
	v_add_co_u32_e32 v38, vcc, 0x7e00000, v62
	s_mov_b32 s15, 0xfbd0000
	s_nop 0
	v_addc_co_u32_e32 v39, vcc, 0, v63, vcc
	global_load_dword v44, v[38:39], off offset:2048
	global_load_dwordx2 v[58:59], v[36:37], off offset:2368
	global_load_dwordx2 v[56:57], v[36:37], off offset:2880
	v_add_co_u32_e32 v36, vcc, 0x7e01000, v34
	s_add_i32 s1, s40, 0xffff8000
	s_nop 0
	v_addc_co_u32_e32 v37, vcc, 0, v35, vcc
	v_add_co_u32_e32 v38, vcc, 0x7e01000, v62
	global_load_dwordx2 v[54:55], v[36:37], off offset:1344
	s_nop 0
	v_addc_co_u32_e32 v39, vcc, 0, v63, vcc
	global_load_dword v60, v[38:39], off offset:1856
	global_load_dwordx2 v[52:53], v[36:37], off offset:2176
	global_load_dwordx2 v[50:51], v[36:37], off offset:2688
	v_add_co_u32_e32 v36, vcc, 0x7e02000, v34
	s_and_b32 s13, s40, 0x1ffc
	s_nop 0
	v_addc_co_u32_e32 v37, vcc, 0, v35, vcc
	v_add_co_u32_e32 v38, vcc, 0x7e02000, v62
	global_load_dwordx2 v[48:49], v[36:37], off offset:1152
	s_nop 0
	v_addc_co_u32_e32 v39, vcc, 0, v63, vcc
	v_add_co_u32_e32 v34, vcc, 0x7e03000, v34
	global_load_dword v17, v[38:39], off offset:1664
	global_load_dwordx2 v[46:47], v[36:37], off offset:1984
	global_load_dwordx2 v[40:41], v[36:37], off offset:2496
	v_addc_co_u32_e32 v35, vcc, 0, v35, vcc
	v_add_co_u32_e32 v36, vcc, 0x7e03000, v62
	global_load_dwordx2 v[38:39], v[34:35], off offset:960
	s_nop 0
	v_addc_co_u32_e32 v37, vcc, 0, v63, vcc
	global_load_dword v15, v[36:37], off offset:1472
	s_nop 0
	global_load_dwordx2 v[36:37], v[34:35], off offset:1792
	s_nop 0
	global_load_dwordx2 v[34:35], v[34:35], off offset:2304
	s_add_i32 s12, s40, 1
	s_add_i32 s3, s40, 2
	s_add_i32 s0, s40, 3
	s_lshr_b32 s1, s1, 8
	s_ashr_i32 s2, s40, 13
	s_addk_i32 s13, 0x100
	s_and_b32 s14, s40, 0xfc
	s_cmp_lt_i32 s40, 0x8000
	s_cselect_b32 s13, s13, s14
	s_cselect_b32 s14, s2, s1
	v_lshl_add_u64 v[30:31], v[30:31], 0, s[48:49]
	v_lshl_add_u64 v[32:33], v[32:33], 0, s[48:49]
	s_waitcnt vmcnt(0)
	v_cvt_f32_f16_e32 v66, v42
	v_cvt_f32_f16_sdwa v67, v42 dst_sel:DWORD dst_unused:UNUSED_PAD src0_sel:WORD_1
	v_cvt_f32_f16_e32 v62, v43
	v_cvt_f32_f16_sdwa v63, v43 dst_sel:DWORD dst_unused:UNUSED_PAD src0_sel:WORD_1
	v_pk_mul_f32 v[42:43], v[66:67], v[66:67]
	s_nop 0
	v_add_f32_e32 v42, v42, v43
	v_pk_mul_f32 v[64:65], v[62:63], v[62:63]
	s_nop 0
	v_add_f32_e32 v42, v64, v42
	v_add_f32_e32 v42, v65, v42
	s_nop 1
	v_add_f32_dpp v42, v42, v42 quad_perm:[1,0,3,2] row_mask:0xf bank_mask:0xf bound_ctrl:1
	s_nop 1
	v_add_f32_dpp v42, v42, v42 quad_perm:[2,3,0,1] row_mask:0xf bank_mask:0xf bound_ctrl:1
	s_nop 1
	v_add_f32_dpp v42, v42, v42 row_half_mirror row_mask:0xf bank_mask:0xf bound_ctrl:1
	s_nop 1
	v_add_f32_dpp v42, v42, v42 row_mirror row_mask:0xf bank_mask:0xf bound_ctrl:1
	v_mov_b32_e32 v43, v42
	s_nop 1
	v_permlane16_swap_b32_e32 v42, v43
	v_add_f32_e32 v42, v42, v43
	v_mov_b32_e32 v43, v42
	s_nop 1
	v_permlane32_swap_b32_e32 v42, v43
	v_add_f32_e32 v42, v42, v43
	v_fmamk_f32 v42, v42, 0x3b800000, v204
	v_cmp_gt_f32_e32 vcc, s80, v42
	v_mul_f32_e32 v43, 0x4f800000, v42
	s_nop 0
	v_cndmask_b32_e32 v42, v42, v43, vcc
	v_sqrt_f32_e32 v43, v42
	s_nop 0
	v_add_u32_e32 v45, -1, v43
	v_fma_f32 v61, -v45, v43, v42
	v_cmp_ge_f32_e64 s[38:39], 0, v61
	v_add_u32_e32 v61, 1, v43
	s_nop 0
	v_cndmask_b32_e64 v45, v43, v45, s[38:39]
	v_fma_f32 v43, -v61, v43, v42
	v_cmp_lt_f32_e64 s[38:39], 0, v43
	s_nop 1
	v_cndmask_b32_e64 v43, v45, v61, s[38:39]
	v_mul_f32_e32 v45, 0x37800000, v43
	v_cndmask_b32_e32 v43, v43, v45, vcc
	v_cmp_class_f32_e32 vcc, v42, v205
	s_nop 1
	v_cndmask_b32_e32 v42, v43, v42, vcc
	v_div_scale_f32 v43, s[20:21], v42, v42, 1.0
	v_rcp_f32_e32 v45, v43
	s_nop 0
	v_fma_f32 v61, -v43, v45, 1.0
	v_fmac_f32_e32 v45, v61, v45
	v_div_scale_f32 v61, vcc, 1.0, v42, 1.0
	v_mul_f32_e32 v64, v61, v45
	v_fma_f32 v65, -v43, v64, v61
	v_fmac_f32_e32 v64, v65, v45
	v_fma_f32 v43, -v43, v64, v61
	v_div_fmas_f32 v43, v43, v45, v64
	v_div_fixup_f32 v42, v43, v42, 1.0
	v_pk_mul_f32 v[64:65], v[42:43], v[66:67] op_sel_hi:[0,1]
	v_pk_mul_f32 v[42:43], v[42:43], v[62:63] op_sel_hi:[0,1]
	v_cvt_f32_f16_e32 v62, v44
	v_cvt_f32_f16_sdwa v63, v44 dst_sel:DWORD dst_unused:UNUSED_PAD src0_sel:WORD_1
	v_pk_mul_f32 v[64:65], v[10:11], v[64:65]
	v_pk_mul_f32 v[42:43], v[12:13], v[42:43]
	v_cvt_pk_f16_f32 v64, v64, v65
	v_pk_mul_f32 v[44:45], v[62:63], v[62:63]
	v_cvt_pk_f16_f32 v65, v42, v43
	v_add_f32_e32 v44, v44, v45
	v_lshl_add_u64 v[42:43], s[10:11], 0, v[28:29]
	v_add_co_u32_e32 v42, vcc, s15, v42
	v_add_f32_dpp v44, v44, v44 quad_perm:[1,0,3,2] row_mask:0xf bank_mask:0xf bound_ctrl:1
	s_nop 0
	v_addc_co_u32_e32 v43, vcc, 0, v43, vcc
	v_add_f32_dpp v44, v44, v44 quad_perm:[2,3,0,1] row_mask:0xf bank_mask:0xf bound_ctrl:1
	global_store_dwordx2 v[42:43], v[64:65], off
	v_cvt_f32_f16_sdwa v67, v58 dst_sel:DWORD dst_unused:UNUSED_PAD src0_sel:WORD_1
	v_add_f32_dpp v44, v44, v44 row_half_mirror row_mask:0xf bank_mask:0xf bound_ctrl:1
	v_lshl_add_u64 v[28:29], v[28:29], 0, s[46:47]
	s_nop 0
	v_add_f32_dpp v44, v44, v44 row_mirror row_mask:0xf bank_mask:0xf bound_ctrl:1
	v_mov_b32_e32 v45, v44
	s_nop 1
	v_permlane16_swap_b32_e32 v44, v45
	v_add_f32_e32 v44, v44, v45
	v_mov_b32_e32 v45, v44
	s_nop 1
	v_permlane32_swap_b32_e32 v44, v45
	v_add_f32_e32 v44, v44, v45
	v_fmamk_f32 v44, v44, 0x3c000000, v204
	v_cmp_gt_f32_e32 vcc, s80, v44
	v_mul_f32_e32 v45, 0x4f800000, v44
	s_nop 0
	v_cndmask_b32_e32 v44, v44, v45, vcc
; __device__ __forceinline__ unsigned pk2(float lo, float hi) { return pg8::cvt_pk_bf16(lo, hi); }
; __device__ __forceinline__ float bflo(unsigned u) { return (float)__builtin_bit_cast(f16x2, u).x; }
; __device__ __forceinline__ float bfhi(unsigned u) { return (float)__builtin_bit_cast(f16x2, u).y; }
; __device__ __forceinline__ float row16_sum(float v) { v += dppf<0xB1>(v); v += dppf<0x4E>(v); v += dppf<0x141>(v); v += dppf<0x140>(v); return v; }
; __device__ __forceinline__ void mixprep_rows(ArgP a, int l, int gw, int NGW, int lane) {
;     ...
;             { const unsigned u = uckv[t4]; float v0 = bflo(u), v1 = bfhi(u);
;               const float rstd = 1.f / sqrtf(wave_sum(v0 * v0 + v1 * v1) * (1.f / 128) + EPS);
;               bf16_t* o = (bf16_t*)(a->ws + OFF_CKVN) + (size_t)row * 256;
;               *(unsigned*)(o + 2 * lane) = pk2(v0 * rstd * gkv0, v1 * rstd * gkv1); *(unsigned*)(o + 128 + 2 * lane) = 0u; }
;             { const u32x2 u = unq[t4]; float v0 = bflo(u.x), v1 = bfhi(u.x), v2 = bflo(u.y), v3 = bfhi(u.y);
;               float sq = v0 * v0 + v1 * v1 + v2 * v2 + v3 * v3; sq = row16_sum(sq);
;               const float rstd = nscale / sqrtf(sq * (1.f / 64) + EPS);
;               u32x2 o; o.x = pk2(v0 * rstd * gnq.x, v1 * rstd * gnq.y); o.y = pk2(v2 * rstd * gnq.z, v3 * rstd * gnq.w);
;               *(u32x2*)((bf16_t*)(a->ws + OFF_NQ) + ((size_t)(b * 4 + hd) * P + p) * 64 + d0) = o; }
;             { const u32x2 u = unk[t4]; float v0 = bflo(u.x), v1 = bfhi(u.x), v2 = bflo(u.y), v3 = bfhi(u.y);
;               float sq = v0 * v0 + v1 * v1 + v2 * v2 + v3 * v3; sq = row16_sum(sq);
;               const float rstd = 1.f / sqrtf(sq * (1.f / 64) + EPS);
;               u32x2 o; o.x = pk2(v0 * rstd * gnk.x, v1 * rstd * gnk.y); o.y = pk2(v2 * rstd * gnk.z, v3 * rstd * gnk.w);
;               *(u32x2*)((bf16_t*)(a->ws + OFF_NK) + ((size_t)(b * 4 + hd) * P + p) * 64 + d0) = o; }
	v_sqrt_f32_e32 v45, v44
	s_nop 0
	v_add_u32_e32 v61, -1, v45
	v_fma_f32 v64, -v61, v45, v44
	v_cmp_ge_f32_e64 s[38:39], 0, v64
	v_add_u32_e32 v64, 1, v45
	s_nop 0
	v_cndmask_b32_e64 v61, v45, v61, s[38:39]
	v_fma_f32 v45, -v64, v45, v44
	v_cmp_lt_f32_e64 s[38:39], 0, v45
	s_nop 1
	v_cndmask_b32_e64 v45, v61, v64, s[38:39]
	v_mul_f32_e32 v61, 0x37800000, v45
	v_cndmask_b32_e32 v45, v45, v61, vcc
	v_cmp_class_f32_e32 vcc, v44, v205
	s_nop 1
	v_cndmask_b32_e32 v44, v45, v44, vcc
	v_div_scale_f32 v45, s[20:21], v44, v44, 1.0
	v_rcp_f32_e32 v61, v45
	s_nop 0
	v_fma_f32 v64, -v45, v61, 1.0
	v_fmac_f32_e32 v61, v64, v61
	v_div_scale_f32 v64, vcc, 1.0, v44, 1.0
	v_mul_f32_e32 v65, v64, v61
	v_fma_f32 v66, -v45, v65, v64
	v_fmac_f32_e32 v65, v66, v61
	v_fma_f32 v45, -v45, v65, v64
	v_div_fmas_f32 v45, v45, v61, v65
	v_div_fixup_f32 v44, v45, v44, 1.0
	v_cvt_f32_f16_e32 v66, v58
	v_pk_mul_f32 v[44:45], v[44:45], v[62:63] op_sel_hi:[0,1]
	v_cvt_f32_f16_e32 v62, v59
	v_cvt_f32_f16_sdwa v63, v59 dst_sel:DWORD dst_unused:UNUSED_PAD src0_sel:WORD_1
	v_pk_mul_f32 v[58:59], v[66:67], v[66:67]
	v_pk_mul_f32 v[44:45], v[20:21], v[44:45]
	v_add_f32_e32 v58, v58, v59
	v_pk_mul_f32 v[64:65], v[62:63], v[62:63]
	v_cvt_pk_f16_f32 v61, v44, v45
	v_add_f32_e32 v58, v64, v58
	v_add_f32_e32 v58, v65, v58
	v_lshl_add_u64 v[44:45], s[10:11], 0, v[26:27]
	v_add_co_u32_e32 v44, vcc, s73, v44
	v_add_f32_dpp v58, v58, v58 quad_perm:[1,0,3,2] row_mask:0xf bank_mask:0xf bound_ctrl:1
	s_nop 0
	v_addc_co_u32_e32 v45, vcc, 0, v45, vcc
	v_add_f32_dpp v58, v58, v58 quad_perm:[2,3,0,1] row_mask:0xf bank_mask:0xf bound_ctrl:1
	global_store_dword v[44:45], v61, off
	v_add_f32_dpp v58, v58, v58 row_half_mirror row_mask:0xf bank_mask:0xf bound_ctrl:1
	v_lshl_add_u64 v[26:27], v[26:27], 0, s[46:47]
	s_nop 0
	v_add_f32_dpp v58, v58, v58 row_mirror row_mask:0xf bank_mask:0xf bound_ctrl:1
	v_fmamk_f32 v58, v58, 0x3c800000, v204
	v_cmp_gt_f32_e32 vcc, s80, v58
	v_mul_f32_e32 v59, 0x4f800000, v58
	s_nop 0
	v_cndmask_b32_e32 v58, v58, v59, vcc
	v_sqrt_f32_e32 v59, v58
	s_nop 0
	v_add_u32_e32 v61, -1, v59
	v_fma_f32 v64, -v61, v59, v58
	v_cmp_ge_f32_e64 s[38:39], 0, v64
	v_add_u32_e32 v64, 1, v59
	s_nop 0
	v_cndmask_b32_e64 v61, v59, v61, s[38:39]
	v_fma_f32 v59, -v64, v59, v58
	v_cmp_lt_f32_e64 s[38:39], 0, v59
	s_nop 1
	v_cndmask_b32_e64 v59, v61, v64, s[38:39]
	v_mul_f32_e32 v61, 0x37800000, v59
	v_cndmask_b32_e32 v59, v59, v61, vcc
	v_cmp_class_f32_e32 vcc, v58, v205
	s_nop 1
	v_cndmask_b32_e32 v58, v59, v58, vcc
	v_div_scale_f32 v59, s[20:21], v58, v58, s67
	v_rcp_f32_e32 v61, v59
	s_nop 0
	v_fma_f32 v64, -v59, v61, 1.0
	v_fmac_f32_e32 v61, v64, v61
	v_div_scale_f32 v64, vcc, s67, v58, s67
	v_mul_f32_e32 v65, v64, v61
	v_fma_f32 v68, -v59, v65, v64
	v_fmac_f32_e32 v65, v68, v61
	v_fma_f32 v59, -v59, v65, v64
	v_div_fmas_f32 v59, v59, v61, v65
	v_div_fixup_f32 v58, v59, v58, s67
	v_pk_mul_f32 v[64:65], v[58:59], v[66:67] op_sel_hi:[0,1]
	v_pk_mul_f32 v[58:59], v[58:59], v[62:63] op_sel_hi:[0,1]
	v_pk_mul_f32 v[64:65], v[6:7], v[64:65]
	v_pk_mul_f32 v[58:59], v[8:9], v[58:59]
	v_cvt_pk_f16_f32 v64, v64, v65
	v_cvt_pk_f16_f32 v65, v58, v59
	v_lshl_add_u32 v61, s14, 2, v1
	v_mov_b32_e32 v58, s13
	v_mov_b32_e32 v59, v0
	v_mad_i64_i32 v[58:59], s[14:15], v61, s76, v[58:59]
	v_lshlrev_b64 v[58:59], 7, v[58:59]
	v_lshl_add_u64 v[62:63], v[22:23], 0, v[58:59]
	v_cvt_f32_f16_e32 v66, v56
	v_cvt_f32_f16_sdwa v67, v56 dst_sel:DWORD dst_unused:UNUSED_PAD src0_sel:WORD_1
	global_store_dwordx2 v[62:63], v[64:65], off
	v_cvt_f32_f16_e32 v62, v57
	v_cvt_f32_f16_sdwa v63, v57 dst_sel:DWORD dst_unused:UNUSED_PAD src0_sel:WORD_1
	v_pk_mul_f32 v[56:57], v[66:67], v[66:67]
	s_and_b32 s13, s12, 0x1ffd
	v_add_f32_e32 v56, v56, v57
	v_pk_mul_f32 v[64:65], v[62:63], v[62:63]
	s_addk_i32 s13, 0x100
	v_add_f32_e32 v56, v64, v56
	v_add_f32_e32 v56, v65, v56
	s_nop 1
	v_add_f32_dpp v56, v56, v56 quad_perm:[1,0,3,2] row_mask:0xf bank_mask:0xf bound_ctrl:1
	s_nop 1
	v_add_f32_dpp v56, v56, v56 quad_perm:[2,3,0,1] row_mask:0xf bank_mask:0xf bound_ctrl:1
	s_nop 1
	v_add_f32_dpp v56, v56, v56 row_half_mirror row_mask:0xf bank_mask:0xf bound_ctrl:1
	s_nop 1
	v_add_f32_dpp v56, v56, v56 row_mirror row_mask:0xf bank_mask:0xf bound_ctrl:1
	v_fmamk_f32 v56, v56, 0x3c800000, v204
	v_cmp_gt_f32_e32 vcc, s80, v56
	v_mul_f32_e32 v57, 0x4f800000, v56
	s_nop 0
	v_cndmask_b32_e32 v56, v56, v57, vcc
	v_sqrt_f32_e32 v57, v56
	s_nop 0
	v_add_u32_e32 v61, -1, v57
	v_fma_f32 v64, -v61, v57, v56
	v_cmp_ge_f32_e64 s[38:39], 0, v64
	v_add_u32_e32 v64, 1, v57
	s_nop 0
	v_cndmask_b32_e64 v61, v57, v61, s[38:39]
	v_fma_f32 v57, -v64, v57, v56
	v_cmp_lt_f32_e64 s[38:39], 0, v57
	s_nop 1
	v_cndmask_b32_e64 v57, v61, v64, s[38:39]
	v_mul_f32_e32 v61, 0x37800000, v57
	v_cndmask_b32_e32 v57, v57, v61, vcc
	v_cmp_class_f32_e32 vcc, v56, v205
	s_nop 1
	v_cndmask_b32_e32 v56, v57, v56, vcc
	v_div_scale_f32 v57, s[14:15], v56, v56, 1.0
	v_rcp_f32_e32 v61, v57
	s_and_b32 s14, s12, 0xfd
	s_cmp_lt_i32 s12, 0x8000
	s_cselect_b32 s14, s13, s14
	v_fma_f32 v64, -v57, v61, 1.0
	v_fmac_f32_e32 v61, v64, v61
	v_div_scale_f32 v64, vcc, 1.0, v56, 1.0
	v_mul_f32_e32 v65, v64, v61
	v_fma_f32 v68, -v57, v65, v64
	v_fmac_f32_e32 v65, v68, v61
	v_fma_f32 v57, -v57, v65, v64
	v_div_fmas_f32 v57, v57, v61, v65
	v_div_fixup_f32 v56, v57, v56, 1.0
	v_pk_mul_f32 v[64:65], v[56:57], v[66:67] op_sel_hi:[0,1]
	v_pk_mul_f32 v[56:57], v[56:57], v[62:63] op_sel_hi:[0,1]
	v_pk_mul_f32 v[64:65], v[2:3], v[64:65]
	v_pk_mul_f32 v[56:57], v[4:5], v[56:57]
	v_cvt_pk_f16_f32 v64, v64, v65
	v_cvt_pk_f16_f32 v65, v56, v57
	v_lshl_add_u64 v[56:57], v[24:25], 0, v[58:59]
; __device__ __forceinline__ unsigned pk2(float lo, float hi) { return pg8::cvt_pk_bf16(lo, hi); }
; __device__ __forceinline__ float bflo(unsigned u) { return (float)__builtin_bit_cast(f16x2, u).x; }
; __device__ __forceinline__ float bfhi(unsigned u) { return (float)__builtin_bit_cast(f16x2, u).y; }
; __device__ __forceinline__ float row16_sum(float v) { v += dppf<0xB1>(v); v += dppf<0x4E>(v); v += dppf<0x141>(v); v += dppf<0x140>(v); return v; }
; __device__ __forceinline__ void mixprep_rows(ArgP a, int l, int gw, int NGW, int lane) {
;     ...
;             { const u32x2 u = ucq[t4]; float v0 = bflo(u.x), v1 = bfhi(u.x), v2 = bflo(u.y), v3 = bfhi(u.y);
;               const float rstd = 1.f / sqrtf(wave_sum(v0 * v0 + v1 * v1 + v2 * v2 + v3 * v3) * (1.f / 256) + EPS);
;               u32x2 o; o.x = pk2(v0 * rstd * gq.x, v1 * rstd * gq.y); o.y = pk2(v2 * rstd * gq.z, v3 * rstd * gq.w);
;               *(u32x2*)((bf16_t*)(a->ws + OFF_CQN) + (size_t)row * 256 + 4 * lane) = o; }
;             { const unsigned u = uckv[t4]; float v0 = bflo(u), v1 = bfhi(u);
;               const float rstd = 1.f / sqrtf(wave_sum(v0 * v0 + v1 * v1) * (1.f / 128) + EPS);
;               bf16_t* o = (bf16_t*)(a->ws + OFF_CKVN) + (size_t)row * 256;
;               *(unsigned*)(o + 2 * lane) = pk2(v0 * rstd * gkv0, v1 * rstd * gkv1); *(unsigned*)(o + 128 + 2 * lane) = 0u; }
;             { const u32x2 u = unq[t4]; float v0 = bflo(u.x), v1 = bfhi(u.x), v2 = bflo(u.y), v3 = bfhi(u.y);
;               float sq = v0 * v0 + v1 * v1 + v2 * v2 + v3 * v3; sq = row16_sum(sq);
;               const float rstd = nscale / sqrtf(sq * (1.f / 64) + EPS);
;               u32x2 o; o.x = pk2(v0 * rstd * gnq.x, v1 * rstd * gnq.y); o.y = pk2(v2 * rstd * gnq.z, v3 * rstd * gnq.w);
;               *(u32x2*)((bf16_t*)(a->ws + OFF_NQ) + ((size_t)(b * 4 + hd) * P + p) * 64 + d0) = o; }
	v_cvt_f32_f16_e32 v62, v54
	v_cvt_f32_f16_sdwa v63, v54 dst_sel:DWORD dst_unused:UNUSED_PAD src0_sel:WORD_1
	global_store_dwordx2 v[56:57], v[64:65], off
	v_cvt_f32_f16_e32 v56, v55
	v_cvt_f32_f16_sdwa v57, v55 dst_sel:DWORD dst_unused:UNUSED_PAD src0_sel:WORD_1
	v_pk_mul_f32 v[54:55], v[62:63], v[62:63]
	s_cselect_b32 s15, s2, s1
	v_add_f32_e32 v54, v54, v55
	v_pk_mul_f32 v[58:59], v[56:57], v[56:57]
	s_nop 0
	v_add_f32_e32 v54, v58, v54
	v_add_f32_e32 v54, v59, v54
	s_nop 1
	v_add_f32_dpp v54, v54, v54 quad_perm:[1,0,3,2] row_mask:0xf bank_mask:0xf bound_ctrl:1
	s_nop 1
	v_add_f32_dpp v54, v54, v54 quad_perm:[2,3,0,1] row_mask:0xf bank_mask:0xf bound_ctrl:1
	s_nop 1
	v_add_f32_dpp v54, v54, v54 row_half_mirror row_mask:0xf bank_mask:0xf bound_ctrl:1
	s_nop 1
	v_add_f32_dpp v54, v54, v54 row_mirror row_mask:0xf bank_mask:0xf bound_ctrl:1
	v_mov_b32_e32 v55, v54
	s_nop 1
	v_permlane16_swap_b32_e32 v54, v55
	v_add_f32_e32 v54, v54, v55
	v_mov_b32_e32 v55, v54
	s_nop 1
	v_permlane32_swap_b32_e32 v54, v55
	v_add_f32_e32 v54, v54, v55
	v_fmamk_f32 v54, v54, 0x3b800000, v204
	v_cmp_gt_f32_e32 vcc, s80, v54
	v_mul_f32_e32 v55, 0x4f800000, v54
	s_nop 0
	v_cndmask_b32_e32 v54, v54, v55, vcc
	v_sqrt_f32_e32 v55, v54
	s_nop 0
	v_add_u32_e32 v58, -1, v55
	v_fma_f32 v59, -v58, v55, v54
	v_cmp_ge_f32_e64 s[38:39], 0, v59
	v_add_u32_e32 v59, 1, v55
	s_nop 0
	v_cndmask_b32_e64 v58, v55, v58, s[38:39]
	v_fma_f32 v55, -v59, v55, v54
	v_cmp_lt_f32_e64 s[38:39], 0, v55
	s_nop 1
	v_cndmask_b32_e64 v55, v58, v59, s[38:39]
	v_mul_f32_e32 v58, 0x37800000, v55
	v_cndmask_b32_e32 v55, v55, v58, vcc
	v_cmp_class_f32_e32 vcc, v54, v205
	s_nop 1
	v_cndmask_b32_e32 v54, v55, v54, vcc
	v_div_scale_f32 v55, s[12:13], v54, v54, 1.0
	v_rcp_f32_e32 v58, v55
	s_nop 0
	v_fma_f32 v59, -v55, v58, 1.0
	v_fmac_f32_e32 v58, v59, v58
	v_div_scale_f32 v59, vcc, 1.0, v54, 1.0
	v_mul_f32_e32 v61, v59, v58
	v_fma_f32 v64, -v55, v61, v59
	v_fmac_f32_e32 v61, v64, v58
	v_fma_f32 v55, -v55, v61, v59
	v_div_fmas_f32 v55, v55, v58, v61
	v_div_fixup_f32 v54, v55, v54, 1.0
	v_pk_mul_f32 v[58:59], v[54:55], v[62:63] op_sel_hi:[0,1]
	v_pk_mul_f32 v[54:55], v[54:55], v[56:57] op_sel_hi:[0,1]
	v_pk_mul_f32 v[58:59], v[10:11], v[58:59]
	v_pk_mul_f32 v[54:55], v[12:13], v[54:55]
	v_cvt_pk_f16_f32 v58, v58, v59
	v_cvt_pk_f16_f32 v59, v54, v55
	v_cvt_f32_f16_e32 v54, v60
	v_cvt_f32_f16_sdwa v55, v60 dst_sel:DWORD dst_unused:UNUSED_PAD src0_sel:WORD_1
	global_store_dwordx2 v[42:43], v[58:59], off offset:512
	v_pk_mul_f32 v[56:57], v[54:55], v[54:55]
	s_nop 0
	v_add_f32_e32 v56, v56, v57
	s_nop 1
	v_add_f32_dpp v56, v56, v56 quad_perm:[1,0,3,2] row_mask:0xf bank_mask:0xf bound_ctrl:1
	s_nop 1
	v_add_f32_dpp v56, v56, v56 quad_perm:[2,3,0,1] row_mask:0xf bank_mask:0xf bound_ctrl:1
	s_nop 1
	v_add_f32_dpp v56, v56, v56 row_half_mirror row_mask:0xf bank_mask:0xf bound_ctrl:1
	s_nop 1
	v_add_f32_dpp v56, v56, v56 row_mirror row_mask:0xf bank_mask:0xf bound_ctrl:1
	v_mov_b32_e32 v57, v56
	s_nop 1
	v_permlane16_swap_b32_e32 v56, v57
	v_add_f32_e32 v56, v56, v57
	v_mov_b32_e32 v57, v56
	s_nop 1
	v_permlane32_swap_b32_e32 v56, v57
	v_add_f32_e32 v56, v56, v57
	v_fmamk_f32 v56, v56, 0x3c000000, v204
	v_cmp_gt_f32_e32 vcc, s80, v56
	v_mul_f32_e32 v57, 0x4f800000, v56
	s_nop 0
	v_cndmask_b32_e32 v56, v56, v57, vcc
	v_sqrt_f32_e32 v57, v56
	s_nop 0
	v_add_u32_e32 v58, -1, v57
	v_fma_f32 v59, -v58, v57, v56
	v_cmp_ge_f32_e64 s[38:39], 0, v59
	v_add_u32_e32 v59, 1, v57
	s_nop 0
	v_cndmask_b32_e64 v58, v57, v58, s[38:39]
	v_fma_f32 v57, -v59, v57, v56
	v_cmp_lt_f32_e64 s[38:39], 0, v57
	s_nop 1
	v_cndmask_b32_e64 v57, v58, v59, s[38:39]
	v_mul_f32_e32 v58, 0x37800000, v57
	v_cndmask_b32_e32 v57, v57, v58, vcc
	v_cmp_class_f32_e32 vcc, v56, v205
	s_nop 1
	v_cndmask_b32_e32 v56, v57, v56, vcc
	v_div_scale_f32 v57, s[12:13], v56, v56, 1.0
	v_rcp_f32_e32 v58, v57
	s_nop 0
	v_fma_f32 v59, -v57, v58, 1.0
	v_fmac_f32_e32 v58, v59, v58
	v_div_scale_f32 v59, vcc, 1.0, v56, 1.0
	v_mul_f32_e32 v60, v59, v58
	v_fma_f32 v61, -v57, v60, v59
	v_fmac_f32_e32 v60, v61, v58
	v_fma_f32 v57, -v57, v60, v59
	v_div_fmas_f32 v57, v57, v58, v60
	v_div_fixup_f32 v56, v57, v56, 1.0
	v_pk_mul_f32 v[54:55], v[56:57], v[54:55] op_sel_hi:[0,1]
	v_pk_mul_f32 v[54:55], v[20:21], v[54:55]
	v_cvt_f32_f16_e32 v58, v52
	v_cvt_pk_f16_f32 v54, v54, v55
	v_cvt_f32_f16_sdwa v59, v52 dst_sel:DWORD dst_unused:UNUSED_PAD src0_sel:WORD_1
	global_store_dword v[44:45], v54, off offset:512
	v_cvt_f32_f16_e32 v54, v53
	v_cvt_f32_f16_sdwa v55, v53 dst_sel:DWORD dst_unused:UNUSED_PAD src0_sel:WORD_1
	v_pk_mul_f32 v[52:53], v[58:59], v[58:59]
	v_pk_mul_f32 v[56:57], v[54:55], v[54:55]
	v_add_f32_e32 v52, v52, v53
	v_add_f32_e32 v52, v56, v52
	v_add_f32_e32 v52, v57, v52
	s_nop 1
	v_add_f32_dpp v52, v52, v52 quad_perm:[1,0,3,2] row_mask:0xf bank_mask:0xf bound_ctrl:1
	s_nop 1
	v_add_f32_dpp v52, v52, v52 quad_perm:[2,3,0,1] row_mask:0xf bank_mask:0xf bound_ctrl:1
	s_nop 1
	v_add_f32_dpp v52, v52, v52 row_half_mirror row_mask:0xf bank_mask:0xf bound_ctrl:1
	s_nop 1
	v_add_f32_dpp v52, v52, v52 row_mirror row_mask:0xf bank_mask:0xf bound_ctrl:1
	v_fmamk_f32 v52, v52, 0x3c800000, v204
	v_cmp_gt_f32_e32 vcc, s80, v52
	v_mul_f32_e32 v53, 0x4f800000, v52
	s_nop 0
	v_cndmask_b32_e32 v52, v52, v53, vcc
	v_sqrt_f32_e32 v53, v52
	s_nop 0
	v_add_u32_e32 v56, -1, v53
	v_fma_f32 v57, -v56, v53, v52
	v_cmp_ge_f32_e64 s[38:39], 0, v57
	v_add_u32_e32 v57, 1, v53
	s_nop 0
	v_cndmask_b32_e64 v56, v53, v56, s[38:39]
	v_fma_f32 v53, -v57, v53, v52
	v_cmp_lt_f32_e64 s[38:39], 0, v53
	s_nop 1
	v_cndmask_b32_e64 v53, v56, v57, s[38:39]
	v_mul_f32_e32 v56, 0x37800000, v53
; __device__ __forceinline__ unsigned pk2(float lo, float hi) { return pg8::cvt_pk_bf16(lo, hi); }
; __device__ __forceinline__ float bflo(unsigned u) { return (float)__builtin_bit_cast(f16x2, u).x; }
; __device__ __forceinline__ float bfhi(unsigned u) { return (float)__builtin_bit_cast(f16x2, u).y; }
; __device__ __forceinline__ float row16_sum(float v) { v += dppf<0xB1>(v); v += dppf<0x4E>(v); v += dppf<0x141>(v); v += dppf<0x140>(v); return v; }
; __device__ __forceinline__ void mixprep_rows(ArgP a, int l, int gw, int NGW, int lane) {
;     ...
;             { const u32x2 u = unq[t4]; float v0 = bflo(u.x), v1 = bfhi(u.x), v2 = bflo(u.y), v3 = bfhi(u.y);
;               float sq = v0 * v0 + v1 * v1 + v2 * v2 + v3 * v3; sq = row16_sum(sq);
;               const float rstd = nscale / sqrtf(sq * (1.f / 64) + EPS);
;               u32x2 o; o.x = pk2(v0 * rstd * gnq.x, v1 * rstd * gnq.y); o.y = pk2(v2 * rstd * gnq.z, v3 * rstd * gnq.w);
;               *(u32x2*)((bf16_t*)(a->ws + OFF_NQ) + ((size_t)(b * 4 + hd) * P + p) * 64 + d0) = o; }
;             { const u32x2 u = unk[t4]; float v0 = bflo(u.x), v1 = bfhi(u.x), v2 = bflo(u.y), v3 = bfhi(u.y);
;               float sq = v0 * v0 + v1 * v1 + v2 * v2 + v3 * v3; sq = row16_sum(sq);
;               const float rstd = 1.f / sqrtf(sq * (1.f / 64) + EPS);
;               u32x2 o; o.x = pk2(v0 * rstd * gnk.x, v1 * rstd * gnk.y); o.y = pk2(v2 * rstd * gnk.z, v3 * rstd * gnk.w);
;               *(u32x2*)((bf16_t*)(a->ws + OFF_NK) + ((size_t)(b * 4 + hd) * P + p) * 64 + d0) = o; }
	v_cndmask_b32_e32 v53, v53, v56, vcc
	v_cmp_class_f32_e32 vcc, v52, v205
	s_nop 1
	v_cndmask_b32_e32 v52, v53, v52, vcc
	v_div_scale_f32 v53, s[12:13], v52, v52, s67
	v_rcp_f32_e32 v56, v53
	s_nop 0
	v_fma_f32 v57, -v53, v56, 1.0
	v_fmac_f32_e32 v56, v57, v56
	v_div_scale_f32 v57, vcc, s67, v52, s67
	v_mul_f32_e32 v60, v57, v56
	v_fma_f32 v61, -v53, v60, v57
	v_fmac_f32_e32 v60, v61, v56
	v_fma_f32 v53, -v53, v60, v57
	v_div_fmas_f32 v53, v53, v56, v60
	v_div_fixup_f32 v56, v53, v52, s67
	v_pk_mul_f32 v[52:53], v[56:57], v[58:59] op_sel_hi:[0,1]
	v_pk_mul_f32 v[54:55], v[56:57], v[54:55] op_sel_hi:[0,1]
	v_pk_mul_f32 v[52:53], v[6:7], v[52:53]
	v_pk_mul_f32 v[54:55], v[8:9], v[54:55]
	v_cvt_pk_f16_f32 v52, v52, v53
	v_cvt_pk_f16_f32 v53, v54, v55
	v_lshl_add_u32 v56, s15, 2, v1
	v_mov_b32_e32 v54, s14
	v_mov_b32_e32 v55, v0
	v_mad_i64_i32 v[54:55], s[12:13], v56, s76, v[54:55]
	v_lshlrev_b64 v[54:55], 7, v[54:55]
	v_lshl_add_u64 v[56:57], v[22:23], 0, v[54:55]
	v_cvt_f32_f16_e32 v58, v50
	v_cvt_f32_f16_sdwa v59, v50 dst_sel:DWORD dst_unused:UNUSED_PAD src0_sel:WORD_1
	global_store_dwordx2 v[56:57], v[52:53], off
	v_cvt_f32_f16_e32 v52, v51
	v_cvt_f32_f16_sdwa v53, v51 dst_sel:DWORD dst_unused:UNUSED_PAD src0_sel:WORD_1
	v_pk_mul_f32 v[50:51], v[58:59], v[58:59]
	v_pk_mul_f32 v[56:57], v[52:53], v[52:53]
	v_add_f32_e32 v50, v50, v51
	v_add_f32_e32 v50, v56, v50
	v_add_f32_e32 v50, v57, v50
	s_nop 1
	v_add_f32_dpp v50, v50, v50 quad_perm:[1,0,3,2] row_mask:0xf bank_mask:0xf bound_ctrl:1
	s_nop 1
	v_add_f32_dpp v50, v50, v50 quad_perm:[2,3,0,1] row_mask:0xf bank_mask:0xf bound_ctrl:1
	s_nop 1
	v_add_f32_dpp v50, v50, v50 row_half_mirror row_mask:0xf bank_mask:0xf bound_ctrl:1
	s_nop 1
	v_add_f32_dpp v50, v50, v50 row_mirror row_mask:0xf bank_mask:0xf bound_ctrl:1
	v_fmamk_f32 v50, v50, 0x3c800000, v204
	v_cmp_gt_f32_e32 vcc, s80, v50
	v_mul_f32_e32 v51, 0x4f800000, v50
	s_nop 0
	v_cndmask_b32_e32 v50, v50, v51, vcc
	v_sqrt_f32_e32 v51, v50
	s_nop 0
	v_add_u32_e32 v56, -1, v51
	v_fma_f32 v57, -v56, v51, v50
	v_cmp_ge_f32_e64 s[38:39], 0, v57
	v_add_u32_e32 v57, 1, v51
	s_nop 0
	v_cndmask_b32_e64 v56, v51, v56, s[38:39]
	v_fma_f32 v51, -v57, v51, v50
	v_cmp_lt_f32_e64 s[38:39], 0, v51
	s_nop 1
	v_cndmask_b32_e64 v51, v56, v57, s[38:39]
	v_mul_f32_e32 v56, 0x37800000, v51
	v_cndmask_b32_e32 v51, v51, v56, vcc
	v_cmp_class_f32_e32 vcc, v50, v205
	s_nop 1
	v_cndmask_b32_e32 v50, v51, v50, vcc
	v_div_scale_f32 v51, s[12:13], v50, v50, 1.0
	v_rcp_f32_e32 v56, v51
	s_and_b32 s12, s3, 0x1ffe
	s_addk_i32 s12, 0x100
	s_and_b32 s13, s3, 0xfe
	v_fma_f32 v57, -v51, v56, 1.0
	v_fmac_f32_e32 v56, v57, v56
	v_div_scale_f32 v57, vcc, 1.0, v50, 1.0
	v_mul_f32_e32 v60, v57, v56
	v_fma_f32 v61, -v51, v60, v57
	v_fmac_f32_e32 v60, v61, v56
	v_fma_f32 v51, -v51, v60, v57
	v_div_fmas_f32 v51, v51, v56, v60
	v_div_fixup_f32 v50, v51, v50, 1.0
	v_pk_mul_f32 v[56:57], v[50:51], v[58:59] op_sel_hi:[0,1]
	v_pk_mul_f32 v[50:51], v[50:51], v[52:53] op_sel_hi:[0,1]
	v_pk_mul_f32 v[56:57], v[2:3], v[56:57]
	v_pk_mul_f32 v[50:51], v[4:5], v[50:51]
	v_cvt_pk_f16_f32 v56, v56, v57
	v_cvt_pk_f16_f32 v57, v50, v51
	v_lshl_add_u64 v[50:51], v[24:25], 0, v[54:55]
	v_cvt_f32_f16_e32 v54, v48
	v_cvt_f32_f16_sdwa v55, v48 dst_sel:DWORD dst_unused:UNUSED_PAD src0_sel:WORD_1
	global_store_dwordx2 v[50:51], v[56:57], off
	v_cvt_f32_f16_e32 v50, v49
	v_cvt_f32_f16_sdwa v51, v49 dst_sel:DWORD dst_unused:UNUSED_PAD src0_sel:WORD_1
	v_pk_mul_f32 v[48:49], v[54:55], v[54:55]
	s_cmp_lt_i32 s3, 0x8000
	v_add_f32_e32 v48, v48, v49
	v_pk_mul_f32 v[52:53], v[50:51], v[50:51]
	s_cselect_b32 s3, s12, s13
	v_add_f32_e32 v48, v52, v48
	v_add_f32_e32 v48, v53, v48
	s_cselect_b32 s14, s2, s1
	s_nop 0
	v_add_f32_dpp v48, v48, v48 quad_perm:[1,0,3,2] row_mask:0xf bank_mask:0xf bound_ctrl:1
	s_nop 1
	v_add_f32_dpp v48, v48, v48 quad_perm:[2,3,0,1] row_mask:0xf bank_mask:0xf bound_ctrl:1
	s_nop 1
	v_add_f32_dpp v48, v48, v48 row_half_mirror row_mask:0xf bank_mask:0xf bound_ctrl:1
	s_nop 1
	v_add_f32_dpp v48, v48, v48 row_mirror row_mask:0xf bank_mask:0xf bound_ctrl:1
	v_mov_b32_e32 v49, v48
	s_nop 1
	v_permlane16_swap_b32_e32 v48, v49
	v_add_f32_e32 v48, v48, v49
	v_mov_b32_e32 v49, v48
	s_nop 1
	v_permlane32_swap_b32_e32 v48, v49
	v_add_f32_e32 v48, v48, v49
	v_fmamk_f32 v48, v48, 0x3b800000, v204
	v_cmp_gt_f32_e32 vcc, s80, v48
	v_mul_f32_e32 v49, 0x4f800000, v48
	s_nop 0
	v_cndmask_b32_e32 v48, v48, v49, vcc
	v_sqrt_f32_e32 v49, v48
	s_nop 0
	v_add_u32_e32 v52, -1, v49
	v_fma_f32 v53, -v52, v49, v48
	v_cmp_ge_f32_e64 s[38:39], 0, v53
	v_add_u32_e32 v53, 1, v49
	s_nop 0
	v_cndmask_b32_e64 v52, v49, v52, s[38:39]
	v_fma_f32 v49, -v53, v49, v48
	v_cmp_lt_f32_e64 s[38:39], 0, v49
	s_nop 1
	v_cndmask_b32_e64 v49, v52, v53, s[38:39]
	v_mul_f32_e32 v52, 0x37800000, v49
	v_cndmask_b32_e32 v49, v49, v52, vcc
	v_cmp_class_f32_e32 vcc, v48, v205
	s_nop 1
	v_cndmask_b32_e32 v48, v49, v48, vcc
	v_div_scale_f32 v49, s[12:13], v48, v48, 1.0
	v_rcp_f32_e32 v52, v49
	s_nop 0
	v_fma_f32 v53, -v49, v52, 1.0
	v_fmac_f32_e32 v52, v53, v52
	v_div_scale_f32 v53, vcc, 1.0, v48, 1.0
	v_mul_f32_e32 v56, v53, v52
	v_fma_f32 v57, -v49, v56, v53
	v_fmac_f32_e32 v56, v57, v52
	v_fma_f32 v49, -v49, v56, v53
	v_div_fmas_f32 v49, v49, v52, v56
	v_div_fixup_f32 v48, v49, v48, 1.0
	v_pk_mul_f32 v[52:53], v[48:49], v[54:55] op_sel_hi:[0,1]
	v_pk_mul_f32 v[48:49], v[48:49], v[50:51] op_sel_hi:[0,1]
	v_pk_mul_f32 v[52:53], v[10:11], v[52:53]
	v_pk_mul_f32 v[48:49], v[12:13], v[48:49]
	v_cvt_pk_f16_f32 v52, v52, v53
	v_cvt_pk_f16_f32 v53, v48, v49
	v_cvt_f32_f16_e32 v48, v17
	v_cvt_f32_f16_sdwa v49, v17 dst_sel:DWORD dst_unused:UNUSED_PAD src0_sel:WORD_1
; __device__ __forceinline__ unsigned pk2(float lo, float hi) { return pg8::cvt_pk_bf16(lo, hi); }
; __device__ __forceinline__ float bflo(unsigned u) { return (float)__builtin_bit_cast(f16x2, u).x; }
; __device__ __forceinline__ float bfhi(unsigned u) { return (float)__builtin_bit_cast(f16x2, u).y; }
; __device__ __forceinline__ float row16_sum(float v) { v += dppf<0xB1>(v); v += dppf<0x4E>(v); v += dppf<0x141>(v); v += dppf<0x140>(v); return v; }
; __device__ __forceinline__ void mixprep_rows(ArgP a, int l, int gw, int NGW, int lane) {
;     ...
;             { const u32x2 u = ucq[t4]; float v0 = bflo(u.x), v1 = bfhi(u.x), v2 = bflo(u.y), v3 = bfhi(u.y);
;               const float rstd = 1.f / sqrtf(wave_sum(v0 * v0 + v1 * v1 + v2 * v2 + v3 * v3) * (1.f / 256) + EPS);
;               u32x2 o; o.x = pk2(v0 * rstd * gq.x, v1 * rstd * gq.y); o.y = pk2(v2 * rstd * gq.z, v3 * rstd * gq.w);
;               *(u32x2*)((bf16_t*)(a->ws + OFF_CQN) + (size_t)row * 256 + 4 * lane) = o; }
;             { const unsigned u = uckv[t4]; float v0 = bflo(u), v1 = bfhi(u);
;               const float rstd = 1.f / sqrtf(wave_sum(v0 * v0 + v1 * v1) * (1.f / 128) + EPS);
;               bf16_t* o = (bf16_t*)(a->ws + OFF_CKVN) + (size_t)row * 256;
;               *(unsigned*)(o + 2 * lane) = pk2(v0 * rstd * gkv0, v1 * rstd * gkv1); *(unsigned*)(o + 128 + 2 * lane) = 0u; }
;             { const u32x2 u = unq[t4]; float v0 = bflo(u.x), v1 = bfhi(u.x), v2 = bflo(u.y), v3 = bfhi(u.y);
;               float sq = v0 * v0 + v1 * v1 + v2 * v2 + v3 * v3; sq = row16_sum(sq);
;               const float rstd = nscale / sqrtf(sq * (1.f / 64) + EPS);
;               u32x2 o; o.x = pk2(v0 * rstd * gnq.x, v1 * rstd * gnq.y); o.y = pk2(v2 * rstd * gnq.z, v3 * rstd * gnq.w);
;               *(u32x2*)((bf16_t*)(a->ws + OFF_NQ) + ((size_t)(b * 4 + hd) * P + p) * 64 + d0) = o; }
;             { const u32x2 u = unk[t4]; float v0 = bflo(u.x), v1 = bfhi(u.x), v2 = bflo(u.y), v3 = bfhi(u.y);
;               float sq = v0 * v0 + v1 * v1 + v2 * v2 + v3 * v3; sq = row16_sum(sq);
;               const float rstd = 1.f / sqrtf(sq * (1.f / 64) + EPS);
;               u32x2 o; o.x = pk2(v0 * rstd * gnk.x, v1 * rstd * gnk.y); o.y = pk2(v2 * rstd * gnk.z, v3 * rstd * gnk.w);
;               *(u32x2*)((bf16_t*)(a->ws + OFF_NK) + ((size_t)(b * 4 + hd) * P + p) * 64 + d0) = o; }
	global_store_dwordx2 v[42:43], v[52:53], off offset:1024
	v_pk_mul_f32 v[50:51], v[48:49], v[48:49]
	s_nop 0
	v_add_f32_e32 v17, v50, v51
	s_nop 1
	v_add_f32_dpp v17, v17, v17 quad_perm:[1,0,3,2] row_mask:0xf bank_mask:0xf bound_ctrl:1
	s_nop 1
	v_add_f32_dpp v17, v17, v17 quad_perm:[2,3,0,1] row_mask:0xf bank_mask:0xf bound_ctrl:1
	s_nop 1
	v_add_f32_dpp v17, v17, v17 row_half_mirror row_mask:0xf bank_mask:0xf bound_ctrl:1
	s_nop 1
	v_add_f32_dpp v17, v17, v17 row_mirror row_mask:0xf bank_mask:0xf bound_ctrl:1
	v_mov_b32_e32 v50, v17
	s_nop 1
	v_permlane16_swap_b32_e32 v17, v50
	v_add_f32_e32 v17, v17, v50
	v_mov_b32_e32 v50, v17
	s_nop 1
	v_permlane32_swap_b32_e32 v17, v50
	v_add_f32_e32 v17, v17, v50
	v_fmamk_f32 v17, v17, 0x3c000000, v204
	v_cmp_gt_f32_e32 vcc, s80, v17
	v_mul_f32_e32 v50, 0x4f800000, v17
	s_nop 0
	v_cndmask_b32_e32 v17, v17, v50, vcc
	v_sqrt_f32_e32 v50, v17
	s_nop 0
	v_add_u32_e32 v51, -1, v50
	v_fma_f32 v52, -v51, v50, v17
	v_cmp_ge_f32_e64 s[38:39], 0, v52
	v_add_u32_e32 v52, 1, v50
	s_nop 0
	v_cndmask_b32_e64 v51, v50, v51, s[38:39]
	v_fma_f32 v50, -v52, v50, v17
	v_cmp_lt_f32_e64 s[38:39], 0, v50
	s_nop 1
	v_cndmask_b32_e64 v50, v51, v52, s[38:39]
	v_mul_f32_e32 v51, 0x37800000, v50
	v_cndmask_b32_e32 v50, v50, v51, vcc
	v_cmp_class_f32_e32 vcc, v17, v205
	s_nop 1
	v_cndmask_b32_e32 v17, v50, v17, vcc
	v_div_scale_f32 v50, s[12:13], v17, v17, 1.0
	v_rcp_f32_e32 v51, v50
	s_nop 0
	v_fma_f32 v52, -v50, v51, 1.0
	v_fmac_f32_e32 v51, v52, v51
	v_div_scale_f32 v52, vcc, 1.0, v17, 1.0
	v_mul_f32_e32 v53, v52, v51
	v_fma_f32 v54, -v50, v53, v52
	v_fmac_f32_e32 v53, v54, v51
	v_fma_f32 v50, -v50, v53, v52
	v_div_fmas_f32 v50, v50, v51, v53
	v_div_fixup_f32 v50, v50, v17, 1.0
	v_pk_mul_f32 v[48:49], v[50:51], v[48:49] op_sel_hi:[0,1]
	v_pk_mul_f32 v[48:49], v[20:21], v[48:49]
	v_cvt_f32_f16_e32 v52, v46
	v_cvt_f32_f16_sdwa v53, v46 dst_sel:DWORD dst_unused:UNUSED_PAD src0_sel:WORD_1
	v_cvt_pk_f16_f32 v17, v48, v49
	v_cvt_f32_f16_e32 v48, v47
	v_cvt_f32_f16_sdwa v49, v47 dst_sel:DWORD dst_unused:UNUSED_PAD src0_sel:WORD_1
	v_pk_mul_f32 v[46:47], v[52:53], v[52:53]
	global_store_dword v[44:45], v17, off offset:1024
	v_add_f32_e32 v17, v46, v47
	v_pk_mul_f32 v[50:51], v[48:49], v[48:49]
	s_nop 0
	v_add_f32_e32 v17, v50, v17
	v_add_f32_e32 v17, v51, v17
	s_nop 1
	v_add_f32_dpp v17, v17, v17 quad_perm:[1,0,3,2] row_mask:0xf bank_mask:0xf bound_ctrl:1
	s_nop 1
	v_add_f32_dpp v17, v17, v17 quad_perm:[2,3,0,1] row_mask:0xf bank_mask:0xf bound_ctrl:1
	s_nop 1
	v_add_f32_dpp v17, v17, v17 row_half_mirror row_mask:0xf bank_mask:0xf bound_ctrl:1
	s_nop 1
	v_add_f32_dpp v17, v17, v17 row_mirror row_mask:0xf bank_mask:0xf bound_ctrl:1
	v_fmamk_f32 v17, v17, 0x3c800000, v204
	v_cmp_gt_f32_e32 vcc, s80, v17
	v_mul_f32_e32 v46, 0x4f800000, v17
	s_nop 0
	v_cndmask_b32_e32 v17, v17, v46, vcc
	v_sqrt_f32_e32 v46, v17
	s_nop 0
	v_add_u32_e32 v47, -1, v46
	v_fma_f32 v50, -v47, v46, v17
	v_cmp_ge_f32_e64 s[38:39], 0, v50
	v_add_u32_e32 v50, 1, v46
	s_nop 0
	v_cndmask_b32_e64 v47, v46, v47, s[38:39]
	v_fma_f32 v46, -v50, v46, v17
	v_cmp_lt_f32_e64 s[38:39], 0, v46
	s_nop 1
	v_cndmask_b32_e64 v46, v47, v50, s[38:39]
	v_mul_f32_e32 v47, 0x37800000, v46
	v_cndmask_b32_e32 v46, v46, v47, vcc
	v_cmp_class_f32_e32 vcc, v17, v205
	s_nop 1
	v_cndmask_b32_e32 v17, v46, v17, vcc
	v_div_scale_f32 v46, s[12:13], v17, v17, s67
	v_rcp_f32_e32 v47, v46
	s_nop 0
	v_fma_f32 v50, -v46, v47, 1.0
	v_fmac_f32_e32 v47, v50, v47
	v_div_scale_f32 v50, vcc, s67, v17, s67
	v_mul_f32_e32 v51, v50, v47
	v_fma_f32 v54, -v46, v51, v50
	v_fmac_f32_e32 v51, v54, v47
	v_fma_f32 v46, -v46, v51, v50
	v_div_fmas_f32 v46, v46, v47, v51
	v_div_fixup_f32 v50, v46, v17, s67
	v_pk_mul_f32 v[46:47], v[50:51], v[52:53] op_sel_hi:[0,1]
	v_pk_mul_f32 v[48:49], v[50:51], v[48:49] op_sel_hi:[0,1]
	v_pk_mul_f32 v[46:47], v[6:7], v[46:47]
	v_pk_mul_f32 v[48:49], v[8:9], v[48:49]
	v_cvt_pk_f16_f32 v46, v46, v47
	v_cvt_pk_f16_f32 v47, v48, v49
	v_lshl_add_u32 v17, s14, 2, v1
	v_mov_b32_e32 v48, s3
	v_mov_b32_e32 v49, v0
	v_mad_i64_i32 v[48:49], s[12:13], v17, s76, v[48:49]
	v_lshlrev_b64 v[48:49], 7, v[48:49]
	v_lshl_add_u64 v[50:51], v[22:23], 0, v[48:49]
	v_cvt_f32_f16_e32 v52, v40
	v_cvt_f32_f16_sdwa v53, v40 dst_sel:DWORD dst_unused:UNUSED_PAD src0_sel:WORD_1
	global_store_dwordx2 v[50:51], v[46:47], off
	v_cvt_f32_f16_e32 v46, v41
	v_cvt_f32_f16_sdwa v47, v41 dst_sel:DWORD dst_unused:UNUSED_PAD src0_sel:WORD_1
	v_pk_mul_f32 v[40:41], v[52:53], v[52:53]
	s_and_b32 s3, s0, 0x1fff
	v_add_f32_e32 v17, v40, v41
	v_pk_mul_f32 v[50:51], v[46:47], v[46:47]
	s_addk_i32 s3, 0x100
	v_add_f32_e32 v17, v50, v17
	v_add_f32_e32 v17, v51, v17
	s_nop 1
	v_add_f32_dpp v17, v17, v17 quad_perm:[1,0,3,2] row_mask:0xf bank_mask:0xf bound_ctrl:1
	s_nop 1
	v_add_f32_dpp v17, v17, v17 quad_perm:[2,3,0,1] row_mask:0xf bank_mask:0xf bound_ctrl:1
	s_nop 1
	v_add_f32_dpp v17, v17, v17 row_half_mirror row_mask:0xf bank_mask:0xf bound_ctrl:1
	s_nop 1
	v_add_f32_dpp v17, v17, v17 row_mirror row_mask:0xf bank_mask:0xf bound_ctrl:1
	v_fmamk_f32 v17, v17, 0x3c800000, v204
	v_cmp_gt_f32_e32 vcc, s80, v17
	v_mul_f32_e32 v40, 0x4f800000, v17
	s_nop 0
	v_cndmask_b32_e32 v17, v17, v40, vcc
	v_sqrt_f32_e32 v40, v17
	s_nop 0
	v_add_u32_e32 v41, -1, v40
	v_fma_f32 v50, -v41, v40, v17
	v_cmp_ge_f32_e64 s[38:39], 0, v50
	v_add_u32_e32 v50, 1, v40
	s_nop 0
	v_cndmask_b32_e64 v41, v40, v41, s[38:39]
	v_fma_f32 v40, -v50, v40, v17
	v_cmp_lt_f32_e64 s[38:39], 0, v40
	s_nop 1
	v_cndmask_b32_e64 v40, v41, v50, s[38:39]
	v_mul_f32_e32 v41, 0x37800000, v40
	v_cndmask_b32_e32 v40, v40, v41, vcc
	v_cmp_class_f32_e32 vcc, v17, v205
	s_nop 1
; __device__ __forceinline__ unsigned pk2(float lo, float hi) { return pg8::cvt_pk_bf16(lo, hi); }
; __device__ __forceinline__ float bflo(unsigned u) { return (float)__builtin_bit_cast(f16x2, u).x; }
; __device__ __forceinline__ float bfhi(unsigned u) { return (float)__builtin_bit_cast(f16x2, u).y; }
; __device__ __forceinline__ float row16_sum(float v) { v += dppf<0xB1>(v); v += dppf<0x4E>(v); v += dppf<0x141>(v); v += dppf<0x140>(v); return v; }
; __device__ __forceinline__ void mixprep_rows(ArgP a, int l, int gw, int NGW, int lane) {
;     ...
;             { const u32x2 u = ucq[t4]; float v0 = bflo(u.x), v1 = bfhi(u.x), v2 = bflo(u.y), v3 = bfhi(u.y);
;               const float rstd = 1.f / sqrtf(wave_sum(v0 * v0 + v1 * v1 + v2 * v2 + v3 * v3) * (1.f / 256) + EPS);
;               u32x2 o; o.x = pk2(v0 * rstd * gq.x, v1 * rstd * gq.y); o.y = pk2(v2 * rstd * gq.z, v3 * rstd * gq.w);
;               *(u32x2*)((bf16_t*)(a->ws + OFF_CQN) + (size_t)row * 256 + 4 * lane) = o; }
;             { const unsigned u = uckv[t4]; float v0 = bflo(u), v1 = bfhi(u);
;               const float rstd = 1.f / sqrtf(wave_sum(v0 * v0 + v1 * v1) * (1.f / 128) + EPS);
;               bf16_t* o = (bf16_t*)(a->ws + OFF_CKVN) + (size_t)row * 256;
;               *(unsigned*)(o + 2 * lane) = pk2(v0 * rstd * gkv0, v1 * rstd * gkv1); *(unsigned*)(o + 128 + 2 * lane) = 0u; }
;             { const u32x2 u = unq[t4]; float v0 = bflo(u.x), v1 = bfhi(u.x), v2 = bflo(u.y), v3 = bfhi(u.y);
;               float sq = v0 * v0 + v1 * v1 + v2 * v2 + v3 * v3; sq = row16_sum(sq);
;               const float rstd = nscale / sqrtf(sq * (1.f / 64) + EPS);
;               u32x2 o; o.x = pk2(v0 * rstd * gnq.x, v1 * rstd * gnq.y); o.y = pk2(v2 * rstd * gnq.z, v3 * rstd * gnq.w);
;               *(u32x2*)((bf16_t*)(a->ws + OFF_NQ) + ((size_t)(b * 4 + hd) * P + p) * 64 + d0) = o; }
;             { const u32x2 u = unk[t4]; float v0 = bflo(u.x), v1 = bfhi(u.x), v2 = bflo(u.y), v3 = bfhi(u.y);
;               float sq = v0 * v0 + v1 * v1 + v2 * v2 + v3 * v3; sq = row16_sum(sq);
;               const float rstd = 1.f / sqrtf(sq * (1.f / 64) + EPS);
;               u32x2 o; o.x = pk2(v0 * rstd * gnk.x, v1 * rstd * gnk.y); o.y = pk2(v2 * rstd * gnk.z, v3 * rstd * gnk.w);
;               *(u32x2*)((bf16_t*)(a->ws + OFF_NK) + ((size_t)(b * 4 + hd) * P + p) * 64 + d0) = o; }
	v_cndmask_b32_e32 v17, v40, v17, vcc
	v_div_scale_f32 v40, s[12:13], v17, v17, 1.0
	v_rcp_f32_e32 v41, v40
	s_and_b32 s12, s0, 0xff
	s_cmp_lt_i32 s0, 0x8000
	s_cselect_b32 s2, s2, s1
	v_fma_f32 v50, -v40, v41, 1.0
	v_fmac_f32_e32 v41, v50, v41
	v_div_scale_f32 v50, vcc, 1.0, v17, 1.0
	v_mul_f32_e32 v51, v50, v41
	v_fma_f32 v54, -v40, v51, v50
	v_fmac_f32_e32 v51, v54, v41
	v_fma_f32 v40, -v40, v51, v50
	v_div_fmas_f32 v40, v40, v41, v51
	v_div_fixup_f32 v40, v40, v17, 1.0
	v_pk_mul_f32 v[50:51], v[40:41], v[52:53] op_sel_hi:[0,1]
	v_pk_mul_f32 v[40:41], v[40:41], v[46:47] op_sel_hi:[0,1]
	v_pk_mul_f32 v[50:51], v[2:3], v[50:51]
	v_pk_mul_f32 v[40:41], v[4:5], v[40:41]
	v_cvt_pk_f16_f32 v50, v50, v51
	v_cvt_pk_f16_f32 v51, v40, v41
	v_lshl_add_u64 v[40:41], v[24:25], 0, v[48:49]
	v_cvt_f32_f16_e32 v48, v38
	v_cvt_f32_f16_sdwa v49, v38 dst_sel:DWORD dst_unused:UNUSED_PAD src0_sel:WORD_1
	global_store_dwordx2 v[40:41], v[50:51], off
	v_cvt_f32_f16_e32 v40, v39
	v_cvt_f32_f16_sdwa v41, v39 dst_sel:DWORD dst_unused:UNUSED_PAD src0_sel:WORD_1
	v_pk_mul_f32 v[38:39], v[48:49], v[48:49]
	s_cselect_b32 s3, s3, s12
	v_add_f32_e32 v17, v38, v39
	v_pk_mul_f32 v[46:47], v[40:41], v[40:41]
	s_add_i32 s40, s40, s42
	v_add_f32_e32 v17, v46, v17
	v_add_f32_e32 v17, v47, v17
	s_cmp_lt_i32 s40, 0x8400
	s_nop 0
	v_add_f32_dpp v17, v17, v17 quad_perm:[1,0,3,2] row_mask:0xf bank_mask:0xf bound_ctrl:1
	s_nop 1
	v_add_f32_dpp v17, v17, v17 quad_perm:[2,3,0,1] row_mask:0xf bank_mask:0xf bound_ctrl:1
	s_nop 1
	v_add_f32_dpp v17, v17, v17 row_half_mirror row_mask:0xf bank_mask:0xf bound_ctrl:1
	s_nop 1
	v_add_f32_dpp v17, v17, v17 row_mirror row_mask:0xf bank_mask:0xf bound_ctrl:1
	v_mov_b32_e32 v38, v17
	s_nop 1
	v_permlane16_swap_b32_e32 v17, v38
	v_add_f32_e32 v17, v17, v38
	v_mov_b32_e32 v38, v17
	s_nop 1
	v_permlane32_swap_b32_e32 v17, v38
	v_add_f32_e32 v17, v17, v38
	v_fmamk_f32 v17, v17, 0x3b800000, v204
	v_cmp_gt_f32_e32 vcc, s80, v17
	v_mul_f32_e32 v38, 0x4f800000, v17
	s_nop 0
	v_cndmask_b32_e32 v17, v17, v38, vcc
	v_sqrt_f32_e32 v38, v17
	s_nop 0
	v_add_u32_e32 v39, -1, v38
	v_fma_f32 v46, -v39, v38, v17
	v_cmp_ge_f32_e64 s[38:39], 0, v46
	v_add_u32_e32 v46, 1, v38
	s_nop 0
	v_cndmask_b32_e64 v39, v38, v39, s[38:39]
	v_fma_f32 v38, -v46, v38, v17
	v_cmp_lt_f32_e64 s[38:39], 0, v38
	s_nop 1
	v_cndmask_b32_e64 v38, v39, v46, s[38:39]
	v_mul_f32_e32 v39, 0x37800000, v38
	v_cndmask_b32_e32 v38, v38, v39, vcc
	v_cmp_class_f32_e32 vcc, v17, v205
	s_nop 1
	v_cndmask_b32_e32 v17, v38, v17, vcc
	v_div_scale_f32 v38, s[0:1], v17, v17, 1.0
	v_rcp_f32_e32 v39, v38
	s_nop 0
	v_fma_f32 v46, -v38, v39, 1.0
	v_fmac_f32_e32 v39, v46, v39
	v_div_scale_f32 v46, vcc, 1.0, v17, 1.0
	v_mul_f32_e32 v47, v46, v39
	v_fma_f32 v50, -v38, v47, v46
	v_fmac_f32_e32 v47, v50, v39
	v_fma_f32 v38, -v38, v47, v46
	v_div_fmas_f32 v38, v38, v39, v47
	v_div_fixup_f32 v38, v38, v17, 1.0
	v_pk_mul_f32 v[46:47], v[38:39], v[48:49] op_sel_hi:[0,1]
	v_pk_mul_f32 v[38:39], v[38:39], v[40:41] op_sel_hi:[0,1]
	v_pk_mul_f32 v[46:47], v[10:11], v[46:47]
	v_pk_mul_f32 v[38:39], v[12:13], v[38:39]
	v_cvt_pk_f16_f32 v46, v46, v47
	v_cvt_pk_f16_f32 v47, v38, v39
	v_cvt_f32_f16_e32 v38, v15
	v_cvt_f32_f16_sdwa v39, v15 dst_sel:DWORD dst_unused:UNUSED_PAD src0_sel:WORD_1
	global_store_dwordx2 v[42:43], v[46:47], off offset:1536
	v_pk_mul_f32 v[40:41], v[38:39], v[38:39]
	s_nop 0
	v_add_f32_e32 v15, v40, v41
	s_nop 1
	v_add_f32_dpp v15, v15, v15 quad_perm:[1,0,3,2] row_mask:0xf bank_mask:0xf bound_ctrl:1
	s_nop 1
	v_add_f32_dpp v15, v15, v15 quad_perm:[2,3,0,1] row_mask:0xf bank_mask:0xf bound_ctrl:1
	s_nop 1
	v_add_f32_dpp v15, v15, v15 row_half_mirror row_mask:0xf bank_mask:0xf bound_ctrl:1
	s_nop 1
	v_add_f32_dpp v15, v15, v15 row_mirror row_mask:0xf bank_mask:0xf bound_ctrl:1
	v_mov_b32_e32 v17, v15
	s_nop 1
	v_permlane16_swap_b32_e32 v15, v17
	v_add_f32_e32 v15, v15, v17
	v_mov_b32_e32 v17, v15
	s_nop 1
	v_permlane32_swap_b32_e32 v15, v17
	v_add_f32_e32 v15, v15, v17
	v_fmamk_f32 v15, v15, 0x3c000000, v204
	v_cmp_gt_f32_e32 vcc, s80, v15
	v_mul_f32_e32 v17, 0x4f800000, v15
	s_nop 0
	v_cndmask_b32_e32 v15, v15, v17, vcc
	v_sqrt_f32_e32 v17, v15
	s_nop 0
	v_add_u32_e32 v40, -1, v17
	v_fma_f32 v41, -v40, v17, v15
	v_cmp_ge_f32_e64 s[38:39], 0, v41
	v_add_u32_e32 v41, 1, v17
	s_nop 0
	v_cndmask_b32_e64 v40, v17, v40, s[38:39]
	v_fma_f32 v17, -v41, v17, v15
	v_cmp_lt_f32_e64 s[38:39], 0, v17
	s_nop 1
	v_cndmask_b32_e64 v17, v40, v41, s[38:39]
	v_mul_f32_e32 v40, 0x37800000, v17
	v_cndmask_b32_e32 v17, v17, v40, vcc
	v_cmp_class_f32_e32 vcc, v15, v205
	s_nop 1
	v_cndmask_b32_e32 v15, v17, v15, vcc
	v_div_scale_f32 v17, s[0:1], v15, v15, 1.0
	v_rcp_f32_e32 v40, v17
	s_nop 0
	v_fma_f32 v41, -v17, v40, 1.0
	v_fmac_f32_e32 v40, v41, v40
	v_div_scale_f32 v41, vcc, 1.0, v15, 1.0
	v_mul_f32_e32 v42, v41, v40
; __device__ __forceinline__ unsigned pk2(float lo, float hi) { return pg8::cvt_pk_bf16(lo, hi); }
; __device__ __forceinline__ float bflo(unsigned u) { return (float)__builtin_bit_cast(f16x2, u).x; }
; __device__ __forceinline__ float bfhi(unsigned u) { return (float)__builtin_bit_cast(f16x2, u).y; }
; __device__ __forceinline__ float row16_sum(float v) { v += dppf<0xB1>(v); v += dppf<0x4E>(v); v += dppf<0x141>(v); v += dppf<0x140>(v); return v; }
; __device__ __forceinline__ void mixprep_rows(ArgP a, int l, int gw, int NGW, int lane) {
;     ...
;             { const u32x2 u = ucq[t4]; float v0 = bflo(u.x), v1 = bfhi(u.x), v2 = bflo(u.y), v3 = bfhi(u.y);
;               const float rstd = 1.f / sqrtf(wave_sum(v0 * v0 + v1 * v1 + v2 * v2 + v3 * v3) * (1.f / 256) + EPS);
;               u32x2 o; o.x = pk2(v0 * rstd * gq.x, v1 * rstd * gq.y); o.y = pk2(v2 * rstd * gq.z, v3 * rstd * gq.w);
;               *(u32x2*)((bf16_t*)(a->ws + OFF_CQN) + (size_t)row * 256 + 4 * lane) = o; }
;             { const unsigned u = uckv[t4]; float v0 = bflo(u), v1 = bfhi(u);
;               const float rstd = 1.f / sqrtf(wave_sum(v0 * v0 + v1 * v1) * (1.f / 128) + EPS);
;               bf16_t* o = (bf16_t*)(a->ws + OFF_CKVN) + (size_t)row * 256;
;               *(unsigned*)(o + 2 * lane) = pk2(v0 * rstd * gkv0, v1 * rstd * gkv1); *(unsigned*)(o + 128 + 2 * lane) = 0u; }
;             { const u32x2 u = unq[t4]; float v0 = bflo(u.x), v1 = bfhi(u.x), v2 = bflo(u.y), v3 = bfhi(u.y);
;               float sq = v0 * v0 + v1 * v1 + v2 * v2 + v3 * v3; sq = row16_sum(sq);
;               const float rstd = nscale / sqrtf(sq * (1.f / 64) + EPS);
;               u32x2 o; o.x = pk2(v0 * rstd * gnq.x, v1 * rstd * gnq.y); o.y = pk2(v2 * rstd * gnq.z, v3 * rstd * gnq.w);
;               *(u32x2*)((bf16_t*)(a->ws + OFF_NQ) + ((size_t)(b * 4 + hd) * P + p) * 64 + d0) = o; }
;             { const u32x2 u = unk[t4]; float v0 = bflo(u.x), v1 = bfhi(u.x), v2 = bflo(u.y), v3 = bfhi(u.y);
;               float sq = v0 * v0 + v1 * v1 + v2 * v2 + v3 * v3; sq = row16_sum(sq);
;               const float rstd = 1.f / sqrtf(sq * (1.f / 64) + EPS);
;               u32x2 o; o.x = pk2(v0 * rstd * gnk.x, v1 * rstd * gnk.y); o.y = pk2(v2 * rstd * gnk.z, v3 * rstd * gnk.w);
;               *(u32x2*)((bf16_t*)(a->ws + OFF_NK) + ((size_t)(b * 4 + hd) * P + p) * 64 + d0) = o; }
;         }
;     }
	v_fma_f32 v43, -v17, v42, v41
	v_fmac_f32_e32 v42, v43, v40
	v_fma_f32 v17, -v17, v42, v41
	v_div_fmas_f32 v17, v17, v40, v42
	v_div_fixup_f32 v40, v17, v15, 1.0
	v_pk_mul_f32 v[38:39], v[40:41], v[38:39] op_sel_hi:[0,1]
	v_pk_mul_f32 v[38:39], v[20:21], v[38:39]
	v_cvt_f32_f16_e32 v42, v36
	v_cvt_f32_f16_sdwa v43, v36 dst_sel:DWORD dst_unused:UNUSED_PAD src0_sel:WORD_1
	v_cvt_pk_f16_f32 v15, v38, v39
	v_cvt_f32_f16_e32 v38, v37
	v_cvt_f32_f16_sdwa v39, v37 dst_sel:DWORD dst_unused:UNUSED_PAD src0_sel:WORD_1
	v_pk_mul_f32 v[36:37], v[42:43], v[42:43]
	global_store_dword v[44:45], v15, off offset:1536
	v_add_f32_e32 v15, v36, v37
	v_pk_mul_f32 v[40:41], v[38:39], v[38:39]
	s_nop 0
	v_add_f32_e32 v15, v40, v15
	v_add_f32_e32 v15, v41, v15
	s_nop 1
	v_add_f32_dpp v15, v15, v15 quad_perm:[1,0,3,2] row_mask:0xf bank_mask:0xf bound_ctrl:1
	s_nop 1
	v_add_f32_dpp v15, v15, v15 quad_perm:[2,3,0,1] row_mask:0xf bank_mask:0xf bound_ctrl:1
	s_nop 1
	v_add_f32_dpp v15, v15, v15 row_half_mirror row_mask:0xf bank_mask:0xf bound_ctrl:1
	s_nop 1
	v_add_f32_dpp v15, v15, v15 row_mirror row_mask:0xf bank_mask:0xf bound_ctrl:1
	v_fmamk_f32 v15, v15, 0x3c800000, v204
	v_cmp_gt_f32_e32 vcc, s80, v15
	v_mul_f32_e32 v17, 0x4f800000, v15
	s_nop 0
	v_cndmask_b32_e32 v15, v15, v17, vcc
	v_sqrt_f32_e32 v17, v15
	s_nop 0
	v_add_u32_e32 v36, -1, v17
	v_fma_f32 v37, -v36, v17, v15
	v_cmp_ge_f32_e64 s[38:39], 0, v37
	v_add_u32_e32 v37, 1, v17
	s_nop 0
	v_cndmask_b32_e64 v36, v17, v36, s[38:39]
	v_fma_f32 v17, -v37, v17, v15
	v_cmp_lt_f32_e64 s[38:39], 0, v17
	s_nop 1
	v_cndmask_b32_e64 v17, v36, v37, s[38:39]
	v_mul_f32_e32 v36, 0x37800000, v17
	v_cndmask_b32_e32 v17, v17, v36, vcc
	v_cmp_class_f32_e32 vcc, v15, v205
	s_nop 1
	v_cndmask_b32_e32 v15, v17, v15, vcc
	v_div_scale_f32 v17, s[0:1], v15, v15, s67
	v_rcp_f32_e32 v36, v17
	s_nop 0
	v_fma_f32 v37, -v17, v36, 1.0
	v_fmac_f32_e32 v36, v37, v36
	v_div_scale_f32 v37, vcc, s67, v15, s67
	v_mul_f32_e32 v40, v37, v36
	v_fma_f32 v41, -v17, v40, v37
	v_fmac_f32_e32 v40, v41, v36
	v_fma_f32 v17, -v17, v40, v37
	v_div_fmas_f32 v17, v17, v36, v40
	v_div_fixup_f32 v40, v17, v15, s67
	v_pk_mul_f32 v[36:37], v[40:41], v[42:43] op_sel_hi:[0,1]
	v_pk_mul_f32 v[38:39], v[40:41], v[38:39] op_sel_hi:[0,1]
	v_pk_mul_f32 v[36:37], v[6:7], v[36:37]
	v_pk_mul_f32 v[38:39], v[8:9], v[38:39]
	v_cvt_pk_f16_f32 v36, v36, v37
	v_cvt_pk_f16_f32 v37, v38, v39
	v_lshl_add_u32 v15, s2, 2, v1
	v_mov_b32_e32 v38, s3
	v_mov_b32_e32 v39, v0
	v_mad_i64_i32 v[38:39], s[0:1], v15, s76, v[38:39]
	v_lshlrev_b64 v[38:39], 7, v[38:39]
	v_lshl_add_u64 v[40:41], v[22:23], 0, v[38:39]
	v_cvt_f32_f16_e32 v42, v34
	v_cvt_f32_f16_sdwa v43, v34 dst_sel:DWORD dst_unused:UNUSED_PAD src0_sel:WORD_1
	global_store_dwordx2 v[40:41], v[36:37], off
	v_cvt_f32_f16_e32 v36, v35
	v_cvt_f32_f16_sdwa v37, v35 dst_sel:DWORD dst_unused:UNUSED_PAD src0_sel:WORD_1
	v_pk_mul_f32 v[34:35], v[42:43], v[42:43]
	v_pk_mul_f32 v[40:41], v[36:37], v[36:37]
	v_add_f32_e32 v15, v34, v35
	v_add_f32_e32 v15, v40, v15
	v_add_f32_e32 v15, v41, v15
	s_nop 1
	v_add_f32_dpp v15, v15, v15 quad_perm:[1,0,3,2] row_mask:0xf bank_mask:0xf bound_ctrl:1
	s_nop 1
	v_add_f32_dpp v15, v15, v15 quad_perm:[2,3,0,1] row_mask:0xf bank_mask:0xf bound_ctrl:1
	s_nop 1
	v_add_f32_dpp v15, v15, v15 row_half_mirror row_mask:0xf bank_mask:0xf bound_ctrl:1
	s_nop 1
	v_add_f32_dpp v15, v15, v15 row_mirror row_mask:0xf bank_mask:0xf bound_ctrl:1
	v_fmamk_f32 v15, v15, 0x3c800000, v204
	v_cmp_gt_f32_e32 vcc, s80, v15
	v_mul_f32_e32 v17, 0x4f800000, v15
	s_nop 0
	v_cndmask_b32_e32 v15, v15, v17, vcc
	v_sqrt_f32_e32 v17, v15
	s_nop 0
	v_add_u32_e32 v34, -1, v17
	v_fma_f32 v35, -v34, v17, v15
	v_cmp_ge_f32_e64 s[38:39], 0, v35
	v_add_u32_e32 v35, 1, v17
	s_nop 0
	v_cndmask_b32_e64 v34, v17, v34, s[38:39]
	v_fma_f32 v17, -v35, v17, v15
	v_cmp_lt_f32_e64 s[38:39], 0, v17
	s_nop 1
	v_cndmask_b32_e64 v17, v34, v35, s[38:39]
	v_mul_f32_e32 v34, 0x37800000, v17
	v_cndmask_b32_e32 v17, v17, v34, vcc
	v_cmp_class_f32_e32 vcc, v15, v205
	s_nop 1
	v_cndmask_b32_e32 v15, v17, v15, vcc
	v_div_scale_f32 v17, s[0:1], v15, v15, 1.0
	v_rcp_f32_e32 v34, v17
	s_nop 0
	v_fma_f32 v35, -v17, v34, 1.0
	v_fmac_f32_e32 v34, v35, v34
	v_div_scale_f32 v35, vcc, 1.0, v15, 1.0
	v_mul_f32_e32 v40, v35, v34
	v_fma_f32 v41, -v17, v40, v35
	v_fmac_f32_e32 v40, v41, v34
	v_fma_f32 v17, -v17, v40, v35
	v_div_fmas_f32 v17, v17, v34, v40
	v_div_fixup_f32 v34, v17, v15, 1.0
	v_pk_mul_f32 v[40:41], v[34:35], v[42:43] op_sel_hi:[0,1]
	v_pk_mul_f32 v[34:35], v[34:35], v[36:37] op_sel_hi:[0,1]
	v_pk_mul_f32 v[40:41], v[2:3], v[40:41]
	v_pk_mul_f32 v[34:35], v[4:5], v[34:35]
	v_cvt_pk_f16_f32 v40, v40, v41
	v_cvt_pk_f16_f32 v41, v34, v35
	v_lshl_add_u64 v[34:35], v[24:25], 0, v[38:39]
	global_store_dwordx2 v[34:35], v[40:41], off
	s_cbranch_scc1 .LBB0_768
